# window branches (NSA window 512 and SWA 128): flash tiles rewritten in place: batched bias reads, unclamped reads + integer masks on boundary tiles, packed sub/sum, no accumulator copies, PV with coun
# speedup vs baseline: 1.0249x; 1.0134x over previous
.LBB0_255:
	s_or_b32 s16, s44, s23
	s_cmp_gt_i32 s16, s18
	s_cbranch_scc1 .LBB0_254
	s_lshl_b32 s16, s16, 14
	s_and_b32 s16, s16, 0xc000
	s_add_i32 s16, s16, 0
	s_waitcnt lgkmcnt(0)
	v_add_u32_e32 v50, s16, v215
	v_and_b32_e32 v51, 64, v147
	v_add_u32_e32 v232, v50, v213
	v_add_u32_e32 v82, 64, v51
	v_add_u32_e32 v165, v50, v214
	ds_read_b128 v[70:73], v232 offset:32768
	ds_read_b128 v[74:77], v232 offset:34816
	ds_read_b128 v[78:81], v165 offset:32768
	ds_read_b128 v[66:69], v165 offset:34816
	ds_read_b128 v[62:65], v232 offset:36864
	ds_read_b128 v[54:57], v232 offset:38912
	ds_read_b128 v[58:61], v165 offset:36864
	ds_read_b128 v[50:53], v165 offset:38912
	s_add_i32 s42, s44, s71
	s_lshl_b32 s82, s42, 6
	s_or_b32 s42, s82, 63
	s_cmp_le_u32 s42, s5
	v_xor_b32_e32 v0, 16, v147
	s_cselect_b64 s[42:43], -1, 0
	s_cmp_gt_i32 s82, s19
	v_cmp_lt_i32_e32 vcc, v0, v82
	v_xor_b32_e32 v83, 32, v147
	s_cselect_b64 s[44:45], -1, 0
	v_cndmask_b32_e32 v0, v147, v0, vcc
	v_cmp_lt_i32_e32 vcc, v83, v82
	s_and_b64 s[42:43], s[42:43], s[44:45]
	v_lshlrev_b32_e32 v0, 2, v0
	v_cndmask_b32_e32 v82, v147, v83, vcc
	v_lshlrev_b32_e32 v149, 2, v82
	s_andn2_b64 vcc, exec, s[42:43]
	s_mov_b64 s[42:43], -1
	s_cbranch_vccz .Lsw_p1
	v_lshl_add_u32 v114, s82, 2, v145
	ds_read2_b32 v[82:83], v114 offset0:127 offset1:128
	ds_read2_b32 v[84:85], v114 offset0:129 offset1:130
	ds_read2_b32 v[86:87], v114 offset0:143 offset1:144
	ds_read2_b32 v[88:89], v114 offset0:145 offset1:146
	s_waitcnt lgkmcnt(4)
	v_mfma_f32_16x16x32_bf16 v[70:73], v[70:73], v[2:5], 0
	v_mfma_f32_16x16x32_bf16 v[74:77], v[74:77], v[2:5], 0
	v_mfma_f32_16x16x32_bf16 v[62:65], v[62:65], v[2:5], 0
	v_mfma_f32_16x16x32_bf16 v[54:57], v[54:57], v[2:5], 0
	ds_read2_b32 v[90:91], v114 offset0:159 offset1:160
	ds_read2_b32 v[92:93], v114 offset0:161 offset1:162
	ds_read2_b32 v[94:95], v114 offset0:175 offset1:176
	ds_read2_b32 v[96:97], v114 offset0:177 offset1:178
	v_mfma_f32_16x16x32_bf16 v[70:73], v[78:81], v[6:9], v[70:73]
	v_mfma_f32_16x16x32_bf16 v[74:77], v[66:69], v[6:9], v[74:77]
	v_mfma_f32_16x16x32_bf16 v[62:65], v[58:61], v[6:9], v[62:65]
	v_mfma_f32_16x16x32_bf16 v[54:57], v[50:53], v[6:9], v[54:57]
	s_waitcnt lgkmcnt(0)
	ds_read_b128 v[98:101], v232 offset:32768
	ds_read_b128 v[78:81], v165 offset:32768
	ds_read_b128 v[102:105], v232 offset:34816
	ds_read_b128 v[66:69], v165 offset:34816
	ds_read_b128 v[106:109], v232 offset:36864
	ds_read_b128 v[58:61], v165 offset:36864
	ds_read_b128 v[110:113], v232 offset:38912
	ds_read_b128 v[50:53], v165 offset:38912
	v_pk_fma_f32 v[70:71], v[70:71], s[36:37], v[82:83] op_sel_hi:[1,0,1]
	v_pk_fma_f32 v[72:73], v[72:73], s[36:37], v[84:85] op_sel_hi:[1,0,1]
	v_pk_fma_f32 v[74:75], v[74:75], s[36:37], v[86:87] op_sel_hi:[1,0,1]
	v_pk_fma_f32 v[76:77], v[76:77], s[36:37], v[88:89] op_sel_hi:[1,0,1]
	v_pk_fma_f32 v[62:63], v[62:63], s[36:37], v[90:91] op_sel_hi:[1,0,1]
	v_pk_fma_f32 v[64:65], v[64:65], s[36:37], v[92:93] op_sel_hi:[1,0,1]
	v_pk_fma_f32 v[54:55], v[54:55], s[36:37], v[94:95] op_sel_hi:[1,0,1]
	v_pk_fma_f32 v[56:57], v[56:57], s[36:37], v[96:97] op_sel_hi:[1,0,1]
	v_or_b32_e32 v117, s82, v216
	v_sub_u32_e32 v115, v144, v117
	v_subrev_u32_e32 v117, 0, v115
	v_cmp_gt_u32_e64 s[48:49], s26, v117
	v_subrev_u32_e32 v117, 1, v115
	v_cmp_gt_u32_e64 s[50:51], s26, v117
	v_subrev_u32_e32 v117, 2, v115
	v_cmp_gt_u32_e64 s[52:53], s26, v117
	v_subrev_u32_e32 v117, 3, v115
	v_cmp_gt_u32_e64 s[54:55], s26, v117
	v_subrev_u32_e32 v117, 16, v115
	v_cmp_gt_u32_e64 s[56:57], s26, v117
	v_subrev_u32_e32 v117, 17, v115
	v_cmp_gt_u32_e64 s[58:59], s26, v117
	v_subrev_u32_e32 v117, 18, v115
	v_cmp_gt_u32_e64 s[60:61], s26, v117
	v_subrev_u32_e32 v117, 19, v115
	v_cmp_gt_u32_e64 s[62:63], s26, v117
	v_cndmask_b32_e64 v70, v148, v70, s[48:49]
	v_cndmask_b32_e64 v71, v148, v71, s[50:51]
	v_cndmask_b32_e64 v72, v148, v72, s[52:53]
	v_cndmask_b32_e64 v73, v148, v73, s[54:55]
	v_cndmask_b32_e64 v74, v148, v74, s[56:57]
	v_cndmask_b32_e64 v75, v148, v75, s[58:59]
	v_cndmask_b32_e64 v76, v148, v76, s[60:61]
	v_cndmask_b32_e64 v77, v148, v77, s[62:63]
	v_subrev_u32_e32 v117, 32, v115
	v_cmp_gt_u32_e64 s[48:49], s26, v117
	v_subrev_u32_e32 v117, 33, v115
	v_cmp_gt_u32_e64 s[50:51], s26, v117
	v_subrev_u32_e32 v117, 34, v115
	v_cmp_gt_u32_e64 s[52:53], s26, v117
	v_subrev_u32_e32 v117, 35, v115
	v_cmp_gt_u32_e64 s[54:55], s26, v117
	v_subrev_u32_e32 v117, 48, v115
	v_cmp_gt_u32_e64 s[56:57], s26, v117
	v_subrev_u32_e32 v117, 49, v115
	v_cmp_gt_u32_e64 s[58:59], s26, v117
	v_subrev_u32_e32 v117, 50, v115
	v_cmp_gt_u32_e64 s[60:61], s26, v117
	v_subrev_u32_e32 v117, 51, v115
	v_cmp_gt_u32_e64 s[62:63], s26, v117
	v_cndmask_b32_e64 v62, v148, v62, s[48:49]
	v_cndmask_b32_e64 v63, v148, v63, s[50:51]
	v_cndmask_b32_e64 v64, v148, v64, s[52:53]
	v_cndmask_b32_e64 v65, v148, v65, s[54:55]
	v_cndmask_b32_e64 v54, v148, v54, s[56:57]
	v_cndmask_b32_e64 v55, v148, v55, s[58:59]
	v_cndmask_b32_e64 v56, v148, v56, s[60:61]
	v_cndmask_b32_e64 v57, v148, v57, s[62:63]
	v_max3_f32 v116, v70, v71, v72
	v_max3_f32 v116, v116, v73, v74
	v_max3_f32 v116, v116, v75, v76
	v_max3_f32 v116, v116, v77, v62
	v_max3_f32 v116, v116, v63, v64
	v_max3_f32 v116, v116, v65, v54
	v_max3_f32 v116, v116, v55, v56
	v_max3_f32 v116, v116, v57, s29
	ds_bpermute_b32 v117, v0, v116
	s_waitcnt lgkmcnt(0)
	v_max_f32_e32 v116, v116, v117
	ds_bpermute_b32 v117, v149, v116
	s_waitcnt lgkmcnt(0)
	v_max_f32_e32 v116, v116, v117
	v_max_f32_e32 v121, v166, v116
	v_sub_f32_e32 v118, v166, v121
	v_cmp_lt_f32_e32 vcc, s30, v121
	v_exp_f32_e32 v118, v118
	v_mov_b32_e32 v166, v121
	v_cndmask_b32_e32 v120, 0, v121, vcc
	v_pk_mul_f32 v[46:47], v[46:47], v[118:119] op_sel_hi:[1,0]
	v_pk_mul_f32 v[48:49], v[48:49], v[118:119] op_sel_hi:[1,0]
	v_pk_mul_f32 v[42:43], v[42:43], v[118:119] op_sel_hi:[1,0]
	v_pk_mul_f32 v[44:45], v[44:45], v[118:119] op_sel_hi:[1,0]
	v_pk_mul_f32 v[38:39], v[38:39], v[118:119] op_sel_hi:[1,0]
	v_pk_mul_f32 v[40:41], v[40:41], v[118:119] op_sel_hi:[1,0]
	v_pk_mul_f32 v[34:35], v[34:35], v[118:119] op_sel_hi:[1,0]
	v_pk_mul_f32 v[36:37], v[36:37], v[118:119] op_sel_hi:[1,0]
	v_pk_add_f32 v[70:71], v[70:71], v[120:121] op_sel_hi:[1,0] neg_lo:[0,1] neg_hi:[0,1]
	v_pk_add_f32 v[72:73], v[72:73], v[120:121] op_sel_hi:[1,0] neg_lo:[0,1] neg_hi:[0,1]
	v_pk_add_f32 v[74:75], v[74:75], v[120:121] op_sel_hi:[1,0] neg_lo:[0,1] neg_hi:[0,1]
	v_pk_add_f32 v[76:77], v[76:77], v[120:121] op_sel_hi:[1,0] neg_lo:[0,1] neg_hi:[0,1]
	v_pk_add_f32 v[62:63], v[62:63], v[120:121] op_sel_hi:[1,0] neg_lo:[0,1] neg_hi:[0,1]
	v_pk_add_f32 v[64:65], v[64:65], v[120:121] op_sel_hi:[1,0] neg_lo:[0,1] neg_hi:[0,1]
	v_pk_add_f32 v[54:55], v[54:55], v[120:121] op_sel_hi:[1,0] neg_lo:[0,1] neg_hi:[0,1]
	v_pk_add_f32 v[56:57], v[56:57], v[120:121] op_sel_hi:[1,0] neg_lo:[0,1] neg_hi:[0,1]
	v_exp_f32_e32 v70, v70
	v_exp_f32_e32 v71, v71
	v_exp_f32_e32 v72, v72
	v_exp_f32_e32 v73, v73
	v_exp_f32_e32 v74, v74
	v_exp_f32_e32 v75, v75
	v_exp_f32_e32 v76, v76
	v_exp_f32_e32 v77, v77
	v_exp_f32_e32 v62, v62
	v_exp_f32_e32 v63, v63
	v_exp_f32_e32 v64, v64
	v_exp_f32_e32 v65, v65
	v_exp_f32_e32 v54, v54
	v_exp_f32_e32 v55, v55
	v_exp_f32_e32 v56, v56
	v_exp_f32_e32 v57, v57
	s_nop 0
	v_pk_add_f32 v[82:83], v[70:71], v[72:73]
	v_pk_add_f32 v[84:85], v[74:75], v[76:77]
	v_pk_add_f32 v[86:87], v[62:63], v[64:65]
	v_pk_add_f32 v[88:89], v[54:55], v[56:57]
	v_pk_add_f32 v[82:83], v[82:83], v[84:85]
	v_pk_add_f32 v[86:87], v[86:87], v[88:89]
	s_nop 0
	v_pk_add_f32 v[82:83], v[82:83], v[86:87]
	s_nop 0
	v_add_f32_e32 v82, v82, v83
	v_fma_f32 v158, v158, v118, v82
	v_cvt_pk_bf16_f32 v77, v76, v77
	v_cvt_pk_bf16_f32 v76, v74, v75
	v_cvt_pk_bf16_f32 v75, v72, v73
	v_cvt_pk_bf16_f32 v74, v70, v71
	v_cvt_pk_bf16_f32 v62, v62, v63
	v_cvt_pk_bf16_f32 v63, v64, v65
	v_cvt_pk_bf16_f32 v64, v54, v55
	v_cvt_pk_bf16_f32 v65, v56, v57
	s_waitcnt lgkmcnt(0)
	ds_read2_b32 v[82:83], v114 offset0:111 offset1:112
	ds_read2_b32 v[84:85], v114 offset0:113 offset1:114
	ds_read2_b32 v[86:87], v114 offset0:127 offset1:128
	ds_read2_b32 v[88:89], v114 offset0:129 offset1:130
	ds_read2_b32 v[90:91], v114 offset0:143 offset1:144
	ds_read2_b32 v[92:93], v114 offset0:145 offset1:146
	ds_read2_b32 v[94:95], v114 offset0:159 offset1:160
	ds_read2_b32 v[96:97], v114 offset0:161 offset1:162
	v_mfma_f32_16x16x32_bf16 v[98:101], v[98:101], v[10:13], 0
	v_mfma_f32_16x16x32_bf16 v[102:105], v[102:105], v[10:13], 0
	v_mfma_f32_16x16x32_bf16 v[106:109], v[106:109], v[10:13], 0
	v_mfma_f32_16x16x32_bf16 v[110:113], v[110:113], v[10:13], 0
	v_mfma_f32_16x16x32_bf16 v[98:101], v[78:81], v[14:17], v[98:101]
	v_mfma_f32_16x16x32_bf16 v[102:105], v[66:69], v[14:17], v[102:105]
	v_mfma_f32_16x16x32_bf16 v[106:109], v[58:61], v[14:17], v[106:109]
	v_mfma_f32_16x16x32_bf16 v[110:113], v[50:53], v[14:17], v[110:113]
	s_waitcnt lgkmcnt(0)
	s_nop 6
	v_pk_fma_f32 v[98:99], v[98:99], s[36:37], v[82:83] op_sel_hi:[1,0,1]
	v_pk_fma_f32 v[100:101], v[100:101], s[36:37], v[84:85] op_sel_hi:[1,0,1]
	v_pk_fma_f32 v[102:103], v[102:103], s[36:37], v[86:87] op_sel_hi:[1,0,1]
	v_pk_fma_f32 v[104:105], v[104:105], s[36:37], v[88:89] op_sel_hi:[1,0,1]
	v_pk_fma_f32 v[106:107], v[106:107], s[36:37], v[90:91] op_sel_hi:[1,0,1]
	v_pk_fma_f32 v[108:109], v[108:109], s[36:37], v[92:93] op_sel_hi:[1,0,1]
	v_pk_fma_f32 v[110:111], v[110:111], s[36:37], v[94:95] op_sel_hi:[1,0,1]
	v_pk_fma_f32 v[112:113], v[112:113], s[36:37], v[96:97] op_sel_hi:[1,0,1]
	v_or_b32_e32 v117, s82, v216
	v_sub_u32_e32 v115, v144, v117
	v_add_u32_e32 v115, 16, v115
	v_subrev_u32_e32 v117, 0, v115
	v_cmp_gt_u32_e64 s[48:49], s26, v117
	v_subrev_u32_e32 v117, 1, v115
	v_cmp_gt_u32_e64 s[50:51], s26, v117
	v_subrev_u32_e32 v117, 2, v115
	v_cmp_gt_u32_e64 s[52:53], s26, v117
	v_subrev_u32_e32 v117, 3, v115
	v_cmp_gt_u32_e64 s[54:55], s26, v117
	v_subrev_u32_e32 v117, 16, v115
	v_cmp_gt_u32_e64 s[56:57], s26, v117
	v_subrev_u32_e32 v117, 17, v115
	v_cmp_gt_u32_e64 s[58:59], s26, v117
	v_subrev_u32_e32 v117, 18, v115
	v_cmp_gt_u32_e64 s[60:61], s26, v117
	v_subrev_u32_e32 v117, 19, v115
	v_cmp_gt_u32_e64 s[62:63], s26, v117
	v_cndmask_b32_e64 v98, v148, v98, s[48:49]
	v_cndmask_b32_e64 v99, v148, v99, s[50:51]
	v_cndmask_b32_e64 v100, v148, v100, s[52:53]
	v_cndmask_b32_e64 v101, v148, v101, s[54:55]
	v_cndmask_b32_e64 v102, v148, v102, s[56:57]
	v_cndmask_b32_e64 v103, v148, v103, s[58:59]
	v_cndmask_b32_e64 v104, v148, v104, s[60:61]
	v_cndmask_b32_e64 v105, v148, v105, s[62:63]
	v_subrev_u32_e32 v117, 32, v115
	v_cmp_gt_u32_e64 s[48:49], s26, v117
	v_subrev_u32_e32 v117, 33, v115
	v_cmp_gt_u32_e64 s[50:51], s26, v117
	v_subrev_u32_e32 v117, 34, v115
	v_cmp_gt_u32_e64 s[52:53], s26, v117
	v_subrev_u32_e32 v117, 35, v115
	v_cmp_gt_u32_e64 s[54:55], s26, v117
	v_subrev_u32_e32 v117, 48, v115
	v_cmp_gt_u32_e64 s[56:57], s26, v117
	v_subrev_u32_e32 v117, 49, v115
	v_cmp_gt_u32_e64 s[58:59], s26, v117
	v_subrev_u32_e32 v117, 50, v115
	v_cmp_gt_u32_e64 s[60:61], s26, v117
	v_subrev_u32_e32 v117, 51, v115
	v_cmp_gt_u32_e64 s[62:63], s26, v117
	v_cndmask_b32_e64 v106, v148, v106, s[48:49]
	v_cndmask_b32_e64 v107, v148, v107, s[50:51]
	v_cndmask_b32_e64 v108, v148, v108, s[52:53]
	v_cndmask_b32_e64 v109, v148, v109, s[54:55]
	v_cndmask_b32_e64 v110, v148, v110, s[56:57]
	v_cndmask_b32_e64 v111, v148, v111, s[58:59]
	v_cndmask_b32_e64 v112, v148, v112, s[60:61]
	v_cndmask_b32_e64 v113, v148, v113, s[62:63]
	v_max3_f32 v116, v98, v99, v100
	v_max3_f32 v116, v116, v101, v102
	v_max3_f32 v116, v116, v103, v104
	v_max3_f32 v116, v116, v105, v106
	v_max3_f32 v116, v116, v107, v108
	v_max3_f32 v116, v116, v109, v110
	v_max3_f32 v116, v116, v111, v112
	v_max3_f32 v116, v116, v113, s29
	ds_bpermute_b32 v117, v0, v116
	s_waitcnt lgkmcnt(0)
	v_max_f32_e32 v116, v116, v117
	ds_bpermute_b32 v117, v149, v116
	s_waitcnt lgkmcnt(0)
	v_max_f32_e32 v116, v116, v117
	v_max_f32_e32 v121, v167, v116
	v_sub_f32_e32 v118, v167, v121
	v_cmp_lt_f32_e32 vcc, s30, v121
	v_exp_f32_e32 v118, v118
	v_mov_b32_e32 v167, v121
	v_cndmask_b32_e32 v120, 0, v121, vcc
	v_pk_mul_f32 v[30:31], v[30:31], v[118:119] op_sel_hi:[1,0]
	v_pk_mul_f32 v[32:33], v[32:33], v[118:119] op_sel_hi:[1,0]
	v_pk_mul_f32 v[26:27], v[26:27], v[118:119] op_sel_hi:[1,0]
	v_pk_mul_f32 v[28:29], v[28:29], v[118:119] op_sel_hi:[1,0]
	v_pk_mul_f32 v[22:23], v[22:23], v[118:119] op_sel_hi:[1,0]
	v_pk_mul_f32 v[24:25], v[24:25], v[118:119] op_sel_hi:[1,0]
	v_pk_mul_f32 v[18:19], v[18:19], v[118:119] op_sel_hi:[1,0]
	v_pk_mul_f32 v[20:21], v[20:21], v[118:119] op_sel_hi:[1,0]
	v_pk_add_f32 v[98:99], v[98:99], v[120:121] op_sel_hi:[1,0] neg_lo:[0,1] neg_hi:[0,1]
	v_pk_add_f32 v[100:101], v[100:101], v[120:121] op_sel_hi:[1,0] neg_lo:[0,1] neg_hi:[0,1]
	v_pk_add_f32 v[102:103], v[102:103], v[120:121] op_sel_hi:[1,0] neg_lo:[0,1] neg_hi:[0,1]
	v_pk_add_f32 v[104:105], v[104:105], v[120:121] op_sel_hi:[1,0] neg_lo:[0,1] neg_hi:[0,1]
	v_pk_add_f32 v[106:107], v[106:107], v[120:121] op_sel_hi:[1,0] neg_lo:[0,1] neg_hi:[0,1]
	v_pk_add_f32 v[108:109], v[108:109], v[120:121] op_sel_hi:[1,0] neg_lo:[0,1] neg_hi:[0,1]
	v_pk_add_f32 v[110:111], v[110:111], v[120:121] op_sel_hi:[1,0] neg_lo:[0,1] neg_hi:[0,1]
	v_pk_add_f32 v[112:113], v[112:113], v[120:121] op_sel_hi:[1,0] neg_lo:[0,1] neg_hi:[0,1]
	v_exp_f32_e32 v98, v98
	v_exp_f32_e32 v99, v99
	v_exp_f32_e32 v100, v100
	v_exp_f32_e32 v101, v101
	v_exp_f32_e32 v102, v102
	v_exp_f32_e32 v103, v103
	v_exp_f32_e32 v104, v104
	v_exp_f32_e32 v105, v105
	v_exp_f32_e32 v106, v106
	v_exp_f32_e32 v107, v107
	v_exp_f32_e32 v108, v108
	v_exp_f32_e32 v109, v109
	v_exp_f32_e32 v110, v110
	v_exp_f32_e32 v111, v111
	v_exp_f32_e32 v112, v112
	v_exp_f32_e32 v113, v113
	s_nop 0
	v_pk_add_f32 v[82:83], v[98:99], v[100:101]
	v_pk_add_f32 v[84:85], v[102:103], v[104:105]
	v_pk_add_f32 v[86:87], v[106:107], v[108:109]
	v_pk_add_f32 v[88:89], v[110:111], v[112:113]
	v_pk_add_f32 v[82:83], v[82:83], v[84:85]
	v_pk_add_f32 v[86:87], v[86:87], v[88:89]
	s_nop 0
	v_pk_add_f32 v[82:83], v[82:83], v[86:87]
	s_nop 0
	v_add_f32_e32 v82, v82, v83
	v_fma_f32 v159, v159, v118, v82
	v_cvt_pk_bf16_f32 v105, v104, v105
	v_cvt_pk_bf16_f32 v104, v102, v103
	v_cvt_pk_bf16_f32 v103, v100, v101
	v_cvt_pk_bf16_f32 v102, v98, v99
	v_cvt_pk_bf16_f32 v106, v106, v107
	v_cvt_pk_bf16_f32 v107, v108, v109
	v_cvt_pk_bf16_f32 v108, v110, v111
	v_cvt_pk_bf16_f32 v109, v112, v113
	s_branch .Lsw_pv
.Lsw_p1:
	v_lshl_add_u32 v114, s82, 2, v145
	ds_read2_b32 v[82:83], v114 offset0:127 offset1:128
	ds_read2_b32 v[84:85], v114 offset0:129 offset1:130
	ds_read2_b32 v[86:87], v114 offset0:143 offset1:144
	ds_read2_b32 v[88:89], v114 offset0:145 offset1:146
	s_waitcnt lgkmcnt(4)
	v_mfma_f32_16x16x32_bf16 v[70:73], v[70:73], v[2:5], 0
	v_mfma_f32_16x16x32_bf16 v[74:77], v[74:77], v[2:5], 0
	v_mfma_f32_16x16x32_bf16 v[62:65], v[62:65], v[2:5], 0
	v_mfma_f32_16x16x32_bf16 v[54:57], v[54:57], v[2:5], 0
	ds_read2_b32 v[90:91], v114 offset0:159 offset1:160
	ds_read2_b32 v[92:93], v114 offset0:161 offset1:162
	ds_read2_b32 v[94:95], v114 offset0:175 offset1:176
	ds_read2_b32 v[96:97], v114 offset0:177 offset1:178
	v_mfma_f32_16x16x32_bf16 v[70:73], v[78:81], v[6:9], v[70:73]
	v_mfma_f32_16x16x32_bf16 v[74:77], v[66:69], v[6:9], v[74:77]
	v_mfma_f32_16x16x32_bf16 v[62:65], v[58:61], v[6:9], v[62:65]
	v_mfma_f32_16x16x32_bf16 v[54:57], v[50:53], v[6:9], v[54:57]
	s_waitcnt lgkmcnt(0)
	ds_read_b128 v[98:101], v232 offset:32768
	ds_read_b128 v[78:81], v165 offset:32768
	ds_read_b128 v[102:105], v232 offset:34816
	ds_read_b128 v[66:69], v165 offset:34816
	ds_read_b128 v[106:109], v232 offset:36864
	ds_read_b128 v[58:61], v165 offset:36864
	ds_read_b128 v[110:113], v232 offset:38912
	ds_read_b128 v[50:53], v165 offset:38912
	v_pk_fma_f32 v[70:71], v[70:71], s[36:37], v[82:83] op_sel_hi:[1,0,1]
	v_pk_fma_f32 v[72:73], v[72:73], s[36:37], v[84:85] op_sel_hi:[1,0,1]
	v_pk_fma_f32 v[74:75], v[74:75], s[36:37], v[86:87] op_sel_hi:[1,0,1]
	v_pk_fma_f32 v[76:77], v[76:77], s[36:37], v[88:89] op_sel_hi:[1,0,1]
	v_pk_fma_f32 v[62:63], v[62:63], s[36:37], v[90:91] op_sel_hi:[1,0,1]
	v_pk_fma_f32 v[64:65], v[64:65], s[36:37], v[92:93] op_sel_hi:[1,0,1]
	v_pk_fma_f32 v[54:55], v[54:55], s[36:37], v[94:95] op_sel_hi:[1,0,1]
	v_pk_fma_f32 v[56:57], v[56:57], s[36:37], v[96:97] op_sel_hi:[1,0,1]
	v_max3_f32 v116, v70, v71, v72
	v_max3_f32 v116, v116, v73, v74
	v_max3_f32 v116, v116, v75, v76
	v_max3_f32 v116, v116, v77, v62
	v_max3_f32 v116, v116, v63, v64
	v_max3_f32 v116, v116, v65, v54
	v_max3_f32 v116, v116, v55, v56
	v_max3_f32 v116, v116, v57, s29
	ds_bpermute_b32 v117, v0, v116
	s_waitcnt lgkmcnt(0)
	v_max_f32_e32 v116, v116, v117
	ds_bpermute_b32 v117, v149, v116
	s_waitcnt lgkmcnt(0)
	v_max_f32_e32 v116, v116, v117
	v_max_f32_e32 v121, v166, v116
	v_sub_f32_e32 v118, v166, v121
	v_exp_f32_e32 v118, v118
	v_mov_b32_e32 v166, v121
	v_mov_b32_e32 v120, v121
	v_pk_mul_f32 v[46:47], v[46:47], v[118:119] op_sel_hi:[1,0]
	v_pk_mul_f32 v[48:49], v[48:49], v[118:119] op_sel_hi:[1,0]
	v_pk_mul_f32 v[42:43], v[42:43], v[118:119] op_sel_hi:[1,0]
	v_pk_mul_f32 v[44:45], v[44:45], v[118:119] op_sel_hi:[1,0]
	v_pk_mul_f32 v[38:39], v[38:39], v[118:119] op_sel_hi:[1,0]
	v_pk_mul_f32 v[40:41], v[40:41], v[118:119] op_sel_hi:[1,0]
	v_pk_mul_f32 v[34:35], v[34:35], v[118:119] op_sel_hi:[1,0]
	v_pk_mul_f32 v[36:37], v[36:37], v[118:119] op_sel_hi:[1,0]
	v_pk_add_f32 v[70:71], v[70:71], v[120:121] op_sel_hi:[1,0] neg_lo:[0,1] neg_hi:[0,1]
	v_pk_add_f32 v[72:73], v[72:73], v[120:121] op_sel_hi:[1,0] neg_lo:[0,1] neg_hi:[0,1]
	v_pk_add_f32 v[74:75], v[74:75], v[120:121] op_sel_hi:[1,0] neg_lo:[0,1] neg_hi:[0,1]
	v_pk_add_f32 v[76:77], v[76:77], v[120:121] op_sel_hi:[1,0] neg_lo:[0,1] neg_hi:[0,1]
	v_pk_add_f32 v[62:63], v[62:63], v[120:121] op_sel_hi:[1,0] neg_lo:[0,1] neg_hi:[0,1]
	v_pk_add_f32 v[64:65], v[64:65], v[120:121] op_sel_hi:[1,0] neg_lo:[0,1] neg_hi:[0,1]
	v_pk_add_f32 v[54:55], v[54:55], v[120:121] op_sel_hi:[1,0] neg_lo:[0,1] neg_hi:[0,1]
	v_pk_add_f32 v[56:57], v[56:57], v[120:121] op_sel_hi:[1,0] neg_lo:[0,1] neg_hi:[0,1]
	v_exp_f32_e32 v70, v70
	v_exp_f32_e32 v71, v71
	v_exp_f32_e32 v72, v72
	v_exp_f32_e32 v73, v73
	v_exp_f32_e32 v74, v74
	v_exp_f32_e32 v75, v75
	v_exp_f32_e32 v76, v76
	v_exp_f32_e32 v77, v77
	v_exp_f32_e32 v62, v62
	v_exp_f32_e32 v63, v63
	v_exp_f32_e32 v64, v64
	v_exp_f32_e32 v65, v65
	v_exp_f32_e32 v54, v54
	v_exp_f32_e32 v55, v55
	v_exp_f32_e32 v56, v56
	v_exp_f32_e32 v57, v57
	s_nop 0
	v_pk_add_f32 v[82:83], v[70:71], v[72:73]
	v_pk_add_f32 v[84:85], v[74:75], v[76:77]
	v_pk_add_f32 v[86:87], v[62:63], v[64:65]
	v_pk_add_f32 v[88:89], v[54:55], v[56:57]
	v_pk_add_f32 v[82:83], v[82:83], v[84:85]
	v_pk_add_f32 v[86:87], v[86:87], v[88:89]
	s_nop 0
	v_pk_add_f32 v[82:83], v[82:83], v[86:87]
	s_nop 0
	v_add_f32_e32 v82, v82, v83
	v_fma_f32 v158, v158, v118, v82
	v_cvt_pk_bf16_f32 v77, v76, v77
	v_cvt_pk_bf16_f32 v76, v74, v75
	v_cvt_pk_bf16_f32 v75, v72, v73
	v_cvt_pk_bf16_f32 v74, v70, v71
	v_cvt_pk_bf16_f32 v62, v62, v63
	v_cvt_pk_bf16_f32 v63, v64, v65
	v_cvt_pk_bf16_f32 v64, v54, v55
	v_cvt_pk_bf16_f32 v65, v56, v57
	s_waitcnt lgkmcnt(0)
	ds_read2_b32 v[82:83], v114 offset0:111 offset1:112
	ds_read2_b32 v[84:85], v114 offset0:113 offset1:114
	ds_read2_b32 v[86:87], v114 offset0:127 offset1:128
	ds_read2_b32 v[88:89], v114 offset0:129 offset1:130
	ds_read2_b32 v[90:91], v114 offset0:143 offset1:144
	ds_read2_b32 v[92:93], v114 offset0:145 offset1:146
	ds_read2_b32 v[94:95], v114 offset0:159 offset1:160
	ds_read2_b32 v[96:97], v114 offset0:161 offset1:162
	v_mfma_f32_16x16x32_bf16 v[98:101], v[98:101], v[10:13], 0
	v_mfma_f32_16x16x32_bf16 v[102:105], v[102:105], v[10:13], 0
	v_mfma_f32_16x16x32_bf16 v[106:109], v[106:109], v[10:13], 0
	v_mfma_f32_16x16x32_bf16 v[110:113], v[110:113], v[10:13], 0
	v_mfma_f32_16x16x32_bf16 v[98:101], v[78:81], v[14:17], v[98:101]
	v_mfma_f32_16x16x32_bf16 v[102:105], v[66:69], v[14:17], v[102:105]
	v_mfma_f32_16x16x32_bf16 v[106:109], v[58:61], v[14:17], v[106:109]
	v_mfma_f32_16x16x32_bf16 v[110:113], v[50:53], v[14:17], v[110:113]
	s_waitcnt lgkmcnt(0)
	s_nop 6
	v_pk_fma_f32 v[98:99], v[98:99], s[36:37], v[82:83] op_sel_hi:[1,0,1]
	v_pk_fma_f32 v[100:101], v[100:101], s[36:37], v[84:85] op_sel_hi:[1,0,1]
	v_pk_fma_f32 v[102:103], v[102:103], s[36:37], v[86:87] op_sel_hi:[1,0,1]
	v_pk_fma_f32 v[104:105], v[104:105], s[36:37], v[88:89] op_sel_hi:[1,0,1]
	v_pk_fma_f32 v[106:107], v[106:107], s[36:37], v[90:91] op_sel_hi:[1,0,1]
	v_pk_fma_f32 v[108:109], v[108:109], s[36:37], v[92:93] op_sel_hi:[1,0,1]
	v_pk_fma_f32 v[110:111], v[110:111], s[36:37], v[94:95] op_sel_hi:[1,0,1]
	v_pk_fma_f32 v[112:113], v[112:113], s[36:37], v[96:97] op_sel_hi:[1,0,1]
	v_max3_f32 v116, v98, v99, v100
	v_max3_f32 v116, v116, v101, v102
	v_max3_f32 v116, v116, v103, v104
	v_max3_f32 v116, v116, v105, v106
	v_max3_f32 v116, v116, v107, v108
	v_max3_f32 v116, v116, v109, v110
	v_max3_f32 v116, v116, v111, v112
	v_max3_f32 v116, v116, v113, s29
	ds_bpermute_b32 v117, v0, v116
	s_waitcnt lgkmcnt(0)
	v_max_f32_e32 v116, v116, v117
	ds_bpermute_b32 v117, v149, v116
	s_waitcnt lgkmcnt(0)
	v_max_f32_e32 v116, v116, v117
	v_max_f32_e32 v121, v167, v116
	v_sub_f32_e32 v118, v167, v121
	v_exp_f32_e32 v118, v118
	v_mov_b32_e32 v167, v121
	v_mov_b32_e32 v120, v121
	v_pk_mul_f32 v[30:31], v[30:31], v[118:119] op_sel_hi:[1,0]
	v_pk_mul_f32 v[32:33], v[32:33], v[118:119] op_sel_hi:[1,0]
	v_pk_mul_f32 v[26:27], v[26:27], v[118:119] op_sel_hi:[1,0]
	v_pk_mul_f32 v[28:29], v[28:29], v[118:119] op_sel_hi:[1,0]
	v_pk_mul_f32 v[22:23], v[22:23], v[118:119] op_sel_hi:[1,0]
	v_pk_mul_f32 v[24:25], v[24:25], v[118:119] op_sel_hi:[1,0]
	v_pk_mul_f32 v[18:19], v[18:19], v[118:119] op_sel_hi:[1,0]
	v_pk_mul_f32 v[20:21], v[20:21], v[118:119] op_sel_hi:[1,0]
	v_pk_add_f32 v[98:99], v[98:99], v[120:121] op_sel_hi:[1,0] neg_lo:[0,1] neg_hi:[0,1]
	v_pk_add_f32 v[100:101], v[100:101], v[120:121] op_sel_hi:[1,0] neg_lo:[0,1] neg_hi:[0,1]
	v_pk_add_f32 v[102:103], v[102:103], v[120:121] op_sel_hi:[1,0] neg_lo:[0,1] neg_hi:[0,1]
	v_pk_add_f32 v[104:105], v[104:105], v[120:121] op_sel_hi:[1,0] neg_lo:[0,1] neg_hi:[0,1]
	v_pk_add_f32 v[106:107], v[106:107], v[120:121] op_sel_hi:[1,0] neg_lo:[0,1] neg_hi:[0,1]
	v_pk_add_f32 v[108:109], v[108:109], v[120:121] op_sel_hi:[1,0] neg_lo:[0,1] neg_hi:[0,1]
	v_pk_add_f32 v[110:111], v[110:111], v[120:121] op_sel_hi:[1,0] neg_lo:[0,1] neg_hi:[0,1]
	v_pk_add_f32 v[112:113], v[112:113], v[120:121] op_sel_hi:[1,0] neg_lo:[0,1] neg_hi:[0,1]
	v_exp_f32_e32 v98, v98
	v_exp_f32_e32 v99, v99
	v_exp_f32_e32 v100, v100
	v_exp_f32_e32 v101, v101
	v_exp_f32_e32 v102, v102
	v_exp_f32_e32 v103, v103
	v_exp_f32_e32 v104, v104
	v_exp_f32_e32 v105, v105
	v_exp_f32_e32 v106, v106
	v_exp_f32_e32 v107, v107
	v_exp_f32_e32 v108, v108
	v_exp_f32_e32 v109, v109
	v_exp_f32_e32 v110, v110
	v_exp_f32_e32 v111, v111
	v_exp_f32_e32 v112, v112
	v_exp_f32_e32 v113, v113
	s_nop 0
	v_pk_add_f32 v[82:83], v[98:99], v[100:101]
	v_pk_add_f32 v[84:85], v[102:103], v[104:105]
	v_pk_add_f32 v[86:87], v[106:107], v[108:109]
	v_pk_add_f32 v[88:89], v[110:111], v[112:113]
	v_pk_add_f32 v[82:83], v[82:83], v[84:85]
	v_pk_add_f32 v[86:87], v[86:87], v[88:89]
	s_nop 0
	v_pk_add_f32 v[82:83], v[82:83], v[86:87]
	s_nop 0
	v_add_f32_e32 v82, v82, v83
	v_fma_f32 v159, v159, v118, v82
	v_cvt_pk_bf16_f32 v105, v104, v105
	v_cvt_pk_bf16_f32 v104, v102, v103
	v_cvt_pk_bf16_f32 v103, v100, v101
	v_cvt_pk_bf16_f32 v102, v98, v99
	v_cvt_pk_bf16_f32 v106, v106, v107
	v_cvt_pk_bf16_f32 v107, v108, v109
	v_cvt_pk_bf16_f32 v108, v110, v111
	v_cvt_pk_bf16_f32 v109, v112, v113
.Lsw_pv:
	v_add3_u32 v114, s16, v217, v219
	v_add_u32_e32 v115, v114, v220
	v_add_u32_e32 v116, v114, v221
	v_add_u32_e32 v117, v114, v222
	v_add_u32_e32 v119, v114, v223
	ds_read_b64_tr_b16 v[82:83], v115 offset:40960
	ds_read_b64_tr_b16 v[84:85], v115 offset:43008
	ds_read_b64_tr_b16 v[86:87], v116 offset:40960
	ds_read_b64_tr_b16 v[88:89], v116 offset:43008
	ds_read_b64_tr_b16 v[90:91], v117 offset:40960
	ds_read_b64_tr_b16 v[92:93], v117 offset:43008
	ds_read_b64_tr_b16 v[94:95], v119 offset:40960
	ds_read_b64_tr_b16 v[96:97], v119 offset:43008
	s_waitcnt lgkmcnt(6)
	v_mfma_f32_16x16x32_bf16 v[46:49], v[82:85], v[74:77], v[46:49]
	v_mfma_f32_16x16x32_bf16 v[30:33], v[82:85], v[102:105], v[30:33]
	ds_read_b64_tr_b16 v[78:79], v115 offset:45056
	ds_read_b64_tr_b16 v[80:81], v115 offset:47104
	s_waitcnt lgkmcnt(6)
	v_mfma_f32_16x16x32_bf16 v[42:45], v[86:89], v[74:77], v[42:45]
	v_mfma_f32_16x16x32_bf16 v[26:29], v[86:89], v[102:105], v[26:29]
	ds_read_b64_tr_b16 v[66:67], v116 offset:45056
	ds_read_b64_tr_b16 v[68:69], v116 offset:47104
	s_waitcnt lgkmcnt(6)
	v_mfma_f32_16x16x32_bf16 v[38:41], v[90:93], v[74:77], v[38:41]
	v_mfma_f32_16x16x32_bf16 v[22:25], v[90:93], v[102:105], v[22:25]
	ds_read_b64_tr_b16 v[58:59], v117 offset:45056
	ds_read_b64_tr_b16 v[60:61], v117 offset:47104
	s_waitcnt lgkmcnt(6)
	v_mfma_f32_16x16x32_bf16 v[34:37], v[94:97], v[74:77], v[34:37]
	v_mfma_f32_16x16x32_bf16 v[18:21], v[94:97], v[102:105], v[18:21]
	ds_read_b64_tr_b16 v[50:51], v119 offset:45056
	ds_read_b64_tr_b16 v[52:53], v119 offset:47104
	s_waitcnt lgkmcnt(6)
	v_mfma_f32_16x16x32_bf16 v[46:49], v[78:81], v[62:65], v[46:49]
	v_mfma_f32_16x16x32_bf16 v[30:33], v[78:81], v[106:109], v[30:33]
	s_waitcnt lgkmcnt(4)
	v_mfma_f32_16x16x32_bf16 v[42:45], v[66:69], v[62:65], v[42:45]
	v_mfma_f32_16x16x32_bf16 v[26:29], v[66:69], v[106:109], v[26:29]
	s_waitcnt lgkmcnt(2)
	v_mfma_f32_16x16x32_bf16 v[38:41], v[58:61], v[62:65], v[38:41]
	v_mfma_f32_16x16x32_bf16 v[22:25], v[58:61], v[106:109], v[22:25]
	s_waitcnt lgkmcnt(0)
	v_mfma_f32_16x16x32_bf16 v[34:37], v[50:53], v[62:65], v[34:37]
	v_mfma_f32_16x16x32_bf16 v[18:21], v[50:53], v[106:109], v[18:21]
	s_xor_b64 s[42:43], s[76:77], -1
	s_mov_b32 s44, 1
	s_mov_b64 s[76:77], 0
	s_and_b64 vcc, exec, s[42:43]
	s_cbranch_vccz .LBB0_255

.LBB0_287:
	s_or_b32 s16, s25, s19
	s_cmp_gt_i32 s16, s14
	s_cbranch_scc1 .LBB0_286
	s_lshl_b32 s16, s16, 14
	s_and_b32 s16, s16, 0xc000
	s_add_i32 s16, s16, 0
	s_waitcnt lgkmcnt(0)
	v_add_u32_e32 v50, s16, v215
	v_and_b32_e32 v51, 64, v147
	v_add_u32_e32 v232, v50, v213
	v_add_u32_e32 v82, 64, v51
	v_add_u32_e32 v159, v50, v214
	ds_read_b128 v[78:81], v232 offset:32768
	ds_read_b128 v[70:73], v232 offset:34816
	ds_read_b128 v[74:77], v159 offset:32768
	ds_read_b128 v[66:69], v159 offset:34816
	ds_read_b128 v[62:65], v232 offset:36864
	ds_read_b128 v[54:57], v232 offset:38912
	ds_read_b128 v[58:61], v159 offset:36864
	ds_read_b128 v[50:53], v159 offset:38912
	s_add_i32 s25, s25, s23
	s_lshl_b32 s25, s25, 6
	s_or_b32 s42, s25, 63
	s_cmp_le_i32 s42, s4
	s_cselect_b64 s[42:43], -1, 0
	s_sub_i32 s44, s18, s25
	v_xor_b32_e32 v0, 16, v147
	s_cmpk_lt_i32 s44, 0x200
	v_cmp_lt_i32_e32 vcc, v0, v82
	v_xor_b32_e32 v83, 32, v147
	s_cselect_b64 s[44:45], -1, 0
	v_cndmask_b32_e32 v0, v147, v0, vcc
	v_cmp_lt_i32_e32 vcc, v83, v82
	s_and_b64 s[42:43], s[42:43], s[44:45]
	v_lshlrev_b32_e32 v0, 2, v0
	v_cndmask_b32_e32 v82, v147, v83, vcc
	v_lshlrev_b32_e32 v149, 2, v82
	s_andn2_b64 vcc, exec, s[42:43]
	s_mov_b64 s[42:43], -1
	s_cbranch_vccz .Lnw_p1
	v_lshl_add_u32 v114, s25, 2, v145
	v_add_u32_e32 v115, 0xffc, v114
	ds_read2_b32 v[82:83], v115 offset1:1
	ds_read2_b32 v[84:85], v115 offset0:2 offset1:3
	ds_read2_b32 v[86:87], v115 offset0:16 offset1:17
	ds_read2_b32 v[88:89], v115 offset0:18 offset1:19
	s_waitcnt lgkmcnt(4)
	v_mfma_f32_16x16x32_bf16 v[78:81], v[78:81], v[2:5], 0
	v_mfma_f32_16x16x32_bf16 v[70:73], v[70:73], v[2:5], 0
	v_mfma_f32_16x16x32_bf16 v[62:65], v[62:65], v[2:5], 0
	v_mfma_f32_16x16x32_bf16 v[54:57], v[54:57], v[2:5], 0
	ds_read2_b32 v[90:91], v115 offset0:32 offset1:33
	ds_read2_b32 v[92:93], v115 offset0:34 offset1:35
	ds_read2_b32 v[94:95], v115 offset0:48 offset1:49
	ds_read2_b32 v[96:97], v115 offset0:50 offset1:51
	v_mfma_f32_16x16x32_bf16 v[78:81], v[74:77], v[6:9], v[78:81]
	v_mfma_f32_16x16x32_bf16 v[70:73], v[66:69], v[6:9], v[70:73]
	v_mfma_f32_16x16x32_bf16 v[62:65], v[58:61], v[6:9], v[62:65]
	v_mfma_f32_16x16x32_bf16 v[54:57], v[50:53], v[6:9], v[54:57]
	s_waitcnt lgkmcnt(0)
	ds_read_b128 v[98:101], v232 offset:32768
	ds_read_b128 v[74:77], v159 offset:32768
	ds_read_b128 v[102:105], v232 offset:34816
	ds_read_b128 v[66:69], v159 offset:34816
	ds_read_b128 v[106:109], v232 offset:36864
	ds_read_b128 v[58:61], v159 offset:36864
	ds_read_b128 v[110:113], v232 offset:38912
	ds_read_b128 v[50:53], v159 offset:38912
	v_pk_fma_f32 v[78:79], v[78:79], s[36:37], v[82:83] op_sel_hi:[1,0,1]
	v_pk_fma_f32 v[80:81], v[80:81], s[36:37], v[84:85] op_sel_hi:[1,0,1]
	v_pk_fma_f32 v[70:71], v[70:71], s[36:37], v[86:87] op_sel_hi:[1,0,1]
	v_pk_fma_f32 v[72:73], v[72:73], s[36:37], v[88:89] op_sel_hi:[1,0,1]
	v_pk_fma_f32 v[62:63], v[62:63], s[36:37], v[90:91] op_sel_hi:[1,0,1]
	v_pk_fma_f32 v[64:65], v[64:65], s[36:37], v[92:93] op_sel_hi:[1,0,1]
	v_pk_fma_f32 v[54:55], v[54:55], s[36:37], v[94:95] op_sel_hi:[1,0,1]
	v_pk_fma_f32 v[56:57], v[56:57], s[36:37], v[96:97] op_sel_hi:[1,0,1]
	v_or_b32_e32 v117, s25, v216
	v_sub_u32_e32 v115, v144, v117
	v_subrev_u32_e32 v117, 0, v115
	v_cmp_gt_u32_e64 s[48:49], s3, v117
	v_subrev_u32_e32 v117, 1, v115
	v_cmp_gt_u32_e64 s[50:51], s3, v117
	v_subrev_u32_e32 v117, 2, v115
	v_cmp_gt_u32_e64 s[52:53], s3, v117
	v_subrev_u32_e32 v117, 3, v115
	v_cmp_gt_u32_e64 s[54:55], s3, v117
	v_subrev_u32_e32 v117, 16, v115
	v_cmp_gt_u32_e64 s[56:57], s3, v117
	v_subrev_u32_e32 v117, 17, v115
	v_cmp_gt_u32_e64 s[58:59], s3, v117
	v_subrev_u32_e32 v117, 18, v115
	v_cmp_gt_u32_e64 s[60:61], s3, v117
	v_subrev_u32_e32 v117, 19, v115
	v_cmp_gt_u32_e64 s[62:63], s3, v117
	v_cndmask_b32_e64 v78, v148, v78, s[48:49]
	v_cndmask_b32_e64 v79, v148, v79, s[50:51]
	v_cndmask_b32_e64 v80, v148, v80, s[52:53]
	v_cndmask_b32_e64 v81, v148, v81, s[54:55]
	v_cndmask_b32_e64 v70, v148, v70, s[56:57]
	v_cndmask_b32_e64 v71, v148, v71, s[58:59]
	v_cndmask_b32_e64 v72, v148, v72, s[60:61]
	v_cndmask_b32_e64 v73, v148, v73, s[62:63]
	v_subrev_u32_e32 v117, 32, v115
	v_cmp_gt_u32_e64 s[48:49], s3, v117
	v_subrev_u32_e32 v117, 33, v115
	v_cmp_gt_u32_e64 s[50:51], s3, v117
	v_subrev_u32_e32 v117, 34, v115
	v_cmp_gt_u32_e64 s[52:53], s3, v117
	v_subrev_u32_e32 v117, 35, v115
	v_cmp_gt_u32_e64 s[54:55], s3, v117
	v_subrev_u32_e32 v117, 48, v115
	v_cmp_gt_u32_e64 s[56:57], s3, v117
	v_subrev_u32_e32 v117, 49, v115
	v_cmp_gt_u32_e64 s[58:59], s3, v117
	v_subrev_u32_e32 v117, 50, v115
	v_cmp_gt_u32_e64 s[60:61], s3, v117
	v_subrev_u32_e32 v117, 51, v115
	v_cmp_gt_u32_e64 s[62:63], s3, v117
	v_cndmask_b32_e64 v62, v148, v62, s[48:49]
	v_cndmask_b32_e64 v63, v148, v63, s[50:51]
	v_cndmask_b32_e64 v64, v148, v64, s[52:53]
	v_cndmask_b32_e64 v65, v148, v65, s[54:55]
	v_cndmask_b32_e64 v54, v148, v54, s[56:57]
	v_cndmask_b32_e64 v55, v148, v55, s[58:59]
	v_cndmask_b32_e64 v56, v148, v56, s[60:61]
	v_cndmask_b32_e64 v57, v148, v57, s[62:63]
	v_max3_f32 v116, v78, v79, v80
	v_max3_f32 v116, v116, v81, v70
	v_max3_f32 v116, v116, v71, v72
	v_max3_f32 v116, v116, v73, v62
	v_max3_f32 v116, v116, v63, v64
	v_max3_f32 v116, v116, v65, v54
	v_max3_f32 v116, v116, v55, v56
	v_max3_f32 v116, v116, v57, s29
	ds_bpermute_b32 v117, v0, v116
	s_waitcnt lgkmcnt(0)
	v_max_f32_e32 v116, v116, v117
	ds_bpermute_b32 v117, v149, v116
	s_waitcnt lgkmcnt(0)
	v_max_f32_e32 v116, v116, v117
	v_max_f32_e32 v121, v166, v116
	v_sub_f32_e32 v118, v166, v121
	v_cmp_lt_f32_e32 vcc, s30, v121
	v_exp_f32_e32 v118, v118
	v_mov_b32_e32 v166, v121
	v_cndmask_b32_e32 v120, 0, v121, vcc
	v_pk_mul_f32 v[46:47], v[46:47], v[118:119] op_sel_hi:[1,0]
	v_pk_mul_f32 v[48:49], v[48:49], v[118:119] op_sel_hi:[1,0]
	v_pk_mul_f32 v[42:43], v[42:43], v[118:119] op_sel_hi:[1,0]
	v_pk_mul_f32 v[44:45], v[44:45], v[118:119] op_sel_hi:[1,0]
	v_pk_mul_f32 v[38:39], v[38:39], v[118:119] op_sel_hi:[1,0]
	v_pk_mul_f32 v[40:41], v[40:41], v[118:119] op_sel_hi:[1,0]
	v_pk_mul_f32 v[34:35], v[34:35], v[118:119] op_sel_hi:[1,0]
	v_pk_mul_f32 v[36:37], v[36:37], v[118:119] op_sel_hi:[1,0]
	v_pk_add_f32 v[78:79], v[78:79], v[120:121] op_sel_hi:[1,0] neg_lo:[0,1] neg_hi:[0,1]
	v_pk_add_f32 v[80:81], v[80:81], v[120:121] op_sel_hi:[1,0] neg_lo:[0,1] neg_hi:[0,1]
	v_pk_add_f32 v[70:71], v[70:71], v[120:121] op_sel_hi:[1,0] neg_lo:[0,1] neg_hi:[0,1]
	v_pk_add_f32 v[72:73], v[72:73], v[120:121] op_sel_hi:[1,0] neg_lo:[0,1] neg_hi:[0,1]
	v_pk_add_f32 v[62:63], v[62:63], v[120:121] op_sel_hi:[1,0] neg_lo:[0,1] neg_hi:[0,1]
	v_pk_add_f32 v[64:65], v[64:65], v[120:121] op_sel_hi:[1,0] neg_lo:[0,1] neg_hi:[0,1]
	v_pk_add_f32 v[54:55], v[54:55], v[120:121] op_sel_hi:[1,0] neg_lo:[0,1] neg_hi:[0,1]
	v_pk_add_f32 v[56:57], v[56:57], v[120:121] op_sel_hi:[1,0] neg_lo:[0,1] neg_hi:[0,1]
	v_exp_f32_e32 v78, v78
	v_exp_f32_e32 v79, v79
	v_exp_f32_e32 v80, v80
	v_exp_f32_e32 v81, v81
	v_exp_f32_e32 v70, v70
	v_exp_f32_e32 v71, v71
	v_exp_f32_e32 v72, v72
	v_exp_f32_e32 v73, v73
	v_exp_f32_e32 v62, v62
	v_exp_f32_e32 v63, v63
	v_exp_f32_e32 v64, v64
	v_exp_f32_e32 v65, v65
	v_exp_f32_e32 v54, v54
	v_exp_f32_e32 v55, v55
	v_exp_f32_e32 v56, v56
	v_exp_f32_e32 v57, v57
	s_nop 0
	v_pk_add_f32 v[82:83], v[78:79], v[80:81]
	v_pk_add_f32 v[84:85], v[70:71], v[72:73]
	v_pk_add_f32 v[86:87], v[62:63], v[64:65]
	v_pk_add_f32 v[88:89], v[54:55], v[56:57]
	v_pk_add_f32 v[82:83], v[82:83], v[84:85]
	v_pk_add_f32 v[86:87], v[86:87], v[88:89]
	s_nop 0
	v_pk_add_f32 v[82:83], v[82:83], v[86:87]
	s_nop 0
	v_add_f32_e32 v82, v82, v83
	v_fma_f32 v160, v160, v118, v82
	v_cvt_pk_bf16_f32 v73, v72, v73
	v_cvt_pk_bf16_f32 v72, v70, v71
	v_cvt_pk_bf16_f32 v71, v80, v81
	v_cvt_pk_bf16_f32 v70, v78, v79
	v_cvt_pk_bf16_f32 v62, v62, v63
	v_cvt_pk_bf16_f32 v63, v64, v65
	v_cvt_pk_bf16_f32 v64, v54, v55
	v_cvt_pk_bf16_f32 v65, v56, v57
	v_add_u32_e32 v115, 0xfbc, v114
	s_waitcnt lgkmcnt(0)
	ds_read2_b32 v[82:83], v115 offset1:1
	ds_read2_b32 v[84:85], v115 offset0:2 offset1:3
	ds_read2_b32 v[86:87], v115 offset0:16 offset1:17
	ds_read2_b32 v[88:89], v115 offset0:18 offset1:19
	ds_read2_b32 v[90:91], v115 offset0:32 offset1:33
	ds_read2_b32 v[92:93], v115 offset0:34 offset1:35
	ds_read2_b32 v[94:95], v115 offset0:48 offset1:49
	ds_read2_b32 v[96:97], v115 offset0:50 offset1:51
	v_mfma_f32_16x16x32_bf16 v[98:101], v[98:101], v[10:13], 0
	v_mfma_f32_16x16x32_bf16 v[102:105], v[102:105], v[10:13], 0
	v_mfma_f32_16x16x32_bf16 v[106:109], v[106:109], v[10:13], 0
	v_mfma_f32_16x16x32_bf16 v[110:113], v[110:113], v[10:13], 0
	v_mfma_f32_16x16x32_bf16 v[98:101], v[74:77], v[14:17], v[98:101]
	v_mfma_f32_16x16x32_bf16 v[102:105], v[66:69], v[14:17], v[102:105]
	v_mfma_f32_16x16x32_bf16 v[106:109], v[58:61], v[14:17], v[106:109]
	v_mfma_f32_16x16x32_bf16 v[110:113], v[50:53], v[14:17], v[110:113]
	s_waitcnt lgkmcnt(0)
	s_nop 6
	v_pk_fma_f32 v[98:99], v[98:99], s[36:37], v[82:83] op_sel_hi:[1,0,1]
	v_pk_fma_f32 v[100:101], v[100:101], s[36:37], v[84:85] op_sel_hi:[1,0,1]
	v_pk_fma_f32 v[102:103], v[102:103], s[36:37], v[86:87] op_sel_hi:[1,0,1]
	v_pk_fma_f32 v[104:105], v[104:105], s[36:37], v[88:89] op_sel_hi:[1,0,1]
	v_pk_fma_f32 v[106:107], v[106:107], s[36:37], v[90:91] op_sel_hi:[1,0,1]
	v_pk_fma_f32 v[108:109], v[108:109], s[36:37], v[92:93] op_sel_hi:[1,0,1]
	v_pk_fma_f32 v[110:111], v[110:111], s[36:37], v[94:95] op_sel_hi:[1,0,1]
	v_pk_fma_f32 v[112:113], v[112:113], s[36:37], v[96:97] op_sel_hi:[1,0,1]
	v_or_b32_e32 v117, s25, v216
	v_sub_u32_e32 v115, v144, v117
	v_add_u32_e32 v115, 16, v115
	v_subrev_u32_e32 v117, 0, v115
	v_cmp_gt_u32_e64 s[48:49], s3, v117
	v_subrev_u32_e32 v117, 1, v115
	v_cmp_gt_u32_e64 s[50:51], s3, v117
	v_subrev_u32_e32 v117, 2, v115
	v_cmp_gt_u32_e64 s[52:53], s3, v117
	v_subrev_u32_e32 v117, 3, v115
	v_cmp_gt_u32_e64 s[54:55], s3, v117
	v_subrev_u32_e32 v117, 16, v115
	v_cmp_gt_u32_e64 s[56:57], s3, v117
	v_subrev_u32_e32 v117, 17, v115
	v_cmp_gt_u32_e64 s[58:59], s3, v117
	v_subrev_u32_e32 v117, 18, v115
	v_cmp_gt_u32_e64 s[60:61], s3, v117
	v_subrev_u32_e32 v117, 19, v115
	v_cmp_gt_u32_e64 s[62:63], s3, v117
	v_cndmask_b32_e64 v98, v148, v98, s[48:49]
	v_cndmask_b32_e64 v99, v148, v99, s[50:51]
	v_cndmask_b32_e64 v100, v148, v100, s[52:53]
	v_cndmask_b32_e64 v101, v148, v101, s[54:55]
	v_cndmask_b32_e64 v102, v148, v102, s[56:57]
	v_cndmask_b32_e64 v103, v148, v103, s[58:59]
	v_cndmask_b32_e64 v104, v148, v104, s[60:61]
	v_cndmask_b32_e64 v105, v148, v105, s[62:63]
	v_subrev_u32_e32 v117, 32, v115
	v_cmp_gt_u32_e64 s[48:49], s3, v117
	v_subrev_u32_e32 v117, 33, v115
	v_cmp_gt_u32_e64 s[50:51], s3, v117
	v_subrev_u32_e32 v117, 34, v115
	v_cmp_gt_u32_e64 s[52:53], s3, v117
	v_subrev_u32_e32 v117, 35, v115
	v_cmp_gt_u32_e64 s[54:55], s3, v117
	v_subrev_u32_e32 v117, 48, v115
	v_cmp_gt_u32_e64 s[56:57], s3, v117
	v_subrev_u32_e32 v117, 49, v115
	v_cmp_gt_u32_e64 s[58:59], s3, v117
	v_subrev_u32_e32 v117, 50, v115
	v_cmp_gt_u32_e64 s[60:61], s3, v117
	v_subrev_u32_e32 v117, 51, v115
	v_cmp_gt_u32_e64 s[62:63], s3, v117
	v_cndmask_b32_e64 v106, v148, v106, s[48:49]
	v_cndmask_b32_e64 v107, v148, v107, s[50:51]
	v_cndmask_b32_e64 v108, v148, v108, s[52:53]
	v_cndmask_b32_e64 v109, v148, v109, s[54:55]
	v_cndmask_b32_e64 v110, v148, v110, s[56:57]
	v_cndmask_b32_e64 v111, v148, v111, s[58:59]
	v_cndmask_b32_e64 v112, v148, v112, s[60:61]
	v_cndmask_b32_e64 v113, v148, v113, s[62:63]
	v_max3_f32 v116, v98, v99, v100
	v_max3_f32 v116, v116, v101, v102
	v_max3_f32 v116, v116, v103, v104
	v_max3_f32 v116, v116, v105, v106
	v_max3_f32 v116, v116, v107, v108
	v_max3_f32 v116, v116, v109, v110
	v_max3_f32 v116, v116, v111, v112
	v_max3_f32 v116, v116, v113, s29
	ds_bpermute_b32 v117, v0, v116
	s_waitcnt lgkmcnt(0)
	v_max_f32_e32 v116, v116, v117
	ds_bpermute_b32 v117, v149, v116
	s_waitcnt lgkmcnt(0)
	v_max_f32_e32 v116, v116, v117
	v_max_f32_e32 v121, v167, v116
	v_sub_f32_e32 v118, v167, v121
	v_cmp_lt_f32_e32 vcc, s30, v121
	v_exp_f32_e32 v118, v118
	v_mov_b32_e32 v167, v121
	v_cndmask_b32_e32 v120, 0, v121, vcc
	v_pk_mul_f32 v[30:31], v[30:31], v[118:119] op_sel_hi:[1,0]
	v_pk_mul_f32 v[32:33], v[32:33], v[118:119] op_sel_hi:[1,0]
	v_pk_mul_f32 v[26:27], v[26:27], v[118:119] op_sel_hi:[1,0]
	v_pk_mul_f32 v[28:29], v[28:29], v[118:119] op_sel_hi:[1,0]
	v_pk_mul_f32 v[22:23], v[22:23], v[118:119] op_sel_hi:[1,0]
	v_pk_mul_f32 v[24:25], v[24:25], v[118:119] op_sel_hi:[1,0]
	v_pk_mul_f32 v[18:19], v[18:19], v[118:119] op_sel_hi:[1,0]
	v_pk_mul_f32 v[20:21], v[20:21], v[118:119] op_sel_hi:[1,0]
	v_pk_add_f32 v[98:99], v[98:99], v[120:121] op_sel_hi:[1,0] neg_lo:[0,1] neg_hi:[0,1]
	v_pk_add_f32 v[100:101], v[100:101], v[120:121] op_sel_hi:[1,0] neg_lo:[0,1] neg_hi:[0,1]
	v_pk_add_f32 v[102:103], v[102:103], v[120:121] op_sel_hi:[1,0] neg_lo:[0,1] neg_hi:[0,1]
	v_pk_add_f32 v[104:105], v[104:105], v[120:121] op_sel_hi:[1,0] neg_lo:[0,1] neg_hi:[0,1]
	v_pk_add_f32 v[106:107], v[106:107], v[120:121] op_sel_hi:[1,0] neg_lo:[0,1] neg_hi:[0,1]
	v_pk_add_f32 v[108:109], v[108:109], v[120:121] op_sel_hi:[1,0] neg_lo:[0,1] neg_hi:[0,1]
	v_pk_add_f32 v[110:111], v[110:111], v[120:121] op_sel_hi:[1,0] neg_lo:[0,1] neg_hi:[0,1]
	v_pk_add_f32 v[112:113], v[112:113], v[120:121] op_sel_hi:[1,0] neg_lo:[0,1] neg_hi:[0,1]
	v_exp_f32_e32 v98, v98
	v_exp_f32_e32 v99, v99
	v_exp_f32_e32 v100, v100
	v_exp_f32_e32 v101, v101
	v_exp_f32_e32 v102, v102
	v_exp_f32_e32 v103, v103
	v_exp_f32_e32 v104, v104
	v_exp_f32_e32 v105, v105
	v_exp_f32_e32 v106, v106
	v_exp_f32_e32 v107, v107
	v_exp_f32_e32 v108, v108
	v_exp_f32_e32 v109, v109
	v_exp_f32_e32 v110, v110
	v_exp_f32_e32 v111, v111
	v_exp_f32_e32 v112, v112
	v_exp_f32_e32 v113, v113
	s_nop 0
	v_pk_add_f32 v[82:83], v[98:99], v[100:101]
	v_pk_add_f32 v[84:85], v[102:103], v[104:105]
	v_pk_add_f32 v[86:87], v[106:107], v[108:109]
	v_pk_add_f32 v[88:89], v[110:111], v[112:113]
	v_pk_add_f32 v[82:83], v[82:83], v[84:85]
	v_pk_add_f32 v[86:87], v[86:87], v[88:89]
	s_nop 0
	v_pk_add_f32 v[82:83], v[82:83], v[86:87]
	s_nop 0
	v_add_f32_e32 v82, v82, v83
	v_fma_f32 v161, v161, v118, v82
	v_cvt_pk_bf16_f32 v105, v104, v105
	v_cvt_pk_bf16_f32 v104, v102, v103
	v_cvt_pk_bf16_f32 v103, v100, v101
	v_cvt_pk_bf16_f32 v102, v98, v99
	v_cvt_pk_bf16_f32 v106, v106, v107
	v_cvt_pk_bf16_f32 v107, v108, v109
	v_cvt_pk_bf16_f32 v108, v110, v111
	v_cvt_pk_bf16_f32 v109, v112, v113
	s_branch .Lnw_pv
.Lnw_p1:
	v_lshl_add_u32 v114, s25, 2, v145
	v_add_u32_e32 v115, 0xffc, v114
	ds_read2_b32 v[82:83], v115 offset1:1
	ds_read2_b32 v[84:85], v115 offset0:2 offset1:3
	ds_read2_b32 v[86:87], v115 offset0:16 offset1:17
	ds_read2_b32 v[88:89], v115 offset0:18 offset1:19
	s_waitcnt lgkmcnt(4)
	v_mfma_f32_16x16x32_bf16 v[78:81], v[78:81], v[2:5], 0
	v_mfma_f32_16x16x32_bf16 v[70:73], v[70:73], v[2:5], 0
	v_mfma_f32_16x16x32_bf16 v[62:65], v[62:65], v[2:5], 0
	v_mfma_f32_16x16x32_bf16 v[54:57], v[54:57], v[2:5], 0
	ds_read2_b32 v[90:91], v115 offset0:32 offset1:33
	ds_read2_b32 v[92:93], v115 offset0:34 offset1:35
	ds_read2_b32 v[94:95], v115 offset0:48 offset1:49
	ds_read2_b32 v[96:97], v115 offset0:50 offset1:51
	v_mfma_f32_16x16x32_bf16 v[78:81], v[74:77], v[6:9], v[78:81]
	v_mfma_f32_16x16x32_bf16 v[70:73], v[66:69], v[6:9], v[70:73]
	v_mfma_f32_16x16x32_bf16 v[62:65], v[58:61], v[6:9], v[62:65]
	v_mfma_f32_16x16x32_bf16 v[54:57], v[50:53], v[6:9], v[54:57]
	s_waitcnt lgkmcnt(0)
	ds_read_b128 v[98:101], v232 offset:32768
	ds_read_b128 v[74:77], v159 offset:32768
	ds_read_b128 v[102:105], v232 offset:34816
	ds_read_b128 v[66:69], v159 offset:34816
	ds_read_b128 v[106:109], v232 offset:36864
	ds_read_b128 v[58:61], v159 offset:36864
	ds_read_b128 v[110:113], v232 offset:38912
	ds_read_b128 v[50:53], v159 offset:38912
	v_pk_fma_f32 v[78:79], v[78:79], s[36:37], v[82:83] op_sel_hi:[1,0,1]
	v_pk_fma_f32 v[80:81], v[80:81], s[36:37], v[84:85] op_sel_hi:[1,0,1]
	v_pk_fma_f32 v[70:71], v[70:71], s[36:37], v[86:87] op_sel_hi:[1,0,1]
	v_pk_fma_f32 v[72:73], v[72:73], s[36:37], v[88:89] op_sel_hi:[1,0,1]
	v_pk_fma_f32 v[62:63], v[62:63], s[36:37], v[90:91] op_sel_hi:[1,0,1]
	v_pk_fma_f32 v[64:65], v[64:65], s[36:37], v[92:93] op_sel_hi:[1,0,1]
	v_pk_fma_f32 v[54:55], v[54:55], s[36:37], v[94:95] op_sel_hi:[1,0,1]
	v_pk_fma_f32 v[56:57], v[56:57], s[36:37], v[96:97] op_sel_hi:[1,0,1]
	v_max3_f32 v116, v78, v79, v80
	v_max3_f32 v116, v116, v81, v70
	v_max3_f32 v116, v116, v71, v72
	v_max3_f32 v116, v116, v73, v62
	v_max3_f32 v116, v116, v63, v64
	v_max3_f32 v116, v116, v65, v54
	v_max3_f32 v116, v116, v55, v56
	v_max3_f32 v116, v116, v57, s29
	ds_bpermute_b32 v117, v0, v116
	s_waitcnt lgkmcnt(0)
	v_max_f32_e32 v116, v116, v117
	ds_bpermute_b32 v117, v149, v116
	s_waitcnt lgkmcnt(0)
	v_max_f32_e32 v116, v116, v117
	v_max_f32_e32 v121, v166, v116
	v_sub_f32_e32 v118, v166, v121
	v_exp_f32_e32 v118, v118
	v_mov_b32_e32 v166, v121
	v_mov_b32_e32 v120, v121
	v_pk_mul_f32 v[46:47], v[46:47], v[118:119] op_sel_hi:[1,0]
	v_pk_mul_f32 v[48:49], v[48:49], v[118:119] op_sel_hi:[1,0]
	v_pk_mul_f32 v[42:43], v[42:43], v[118:119] op_sel_hi:[1,0]
	v_pk_mul_f32 v[44:45], v[44:45], v[118:119] op_sel_hi:[1,0]
	v_pk_mul_f32 v[38:39], v[38:39], v[118:119] op_sel_hi:[1,0]
	v_pk_mul_f32 v[40:41], v[40:41], v[118:119] op_sel_hi:[1,0]
	v_pk_mul_f32 v[34:35], v[34:35], v[118:119] op_sel_hi:[1,0]
	v_pk_mul_f32 v[36:37], v[36:37], v[118:119] op_sel_hi:[1,0]
	v_pk_add_f32 v[78:79], v[78:79], v[120:121] op_sel_hi:[1,0] neg_lo:[0,1] neg_hi:[0,1]
	v_pk_add_f32 v[80:81], v[80:81], v[120:121] op_sel_hi:[1,0] neg_lo:[0,1] neg_hi:[0,1]
	v_pk_add_f32 v[70:71], v[70:71], v[120:121] op_sel_hi:[1,0] neg_lo:[0,1] neg_hi:[0,1]
	v_pk_add_f32 v[72:73], v[72:73], v[120:121] op_sel_hi:[1,0] neg_lo:[0,1] neg_hi:[0,1]
	v_pk_add_f32 v[62:63], v[62:63], v[120:121] op_sel_hi:[1,0] neg_lo:[0,1] neg_hi:[0,1]
	v_pk_add_f32 v[64:65], v[64:65], v[120:121] op_sel_hi:[1,0] neg_lo:[0,1] neg_hi:[0,1]
	v_pk_add_f32 v[54:55], v[54:55], v[120:121] op_sel_hi:[1,0] neg_lo:[0,1] neg_hi:[0,1]
	v_pk_add_f32 v[56:57], v[56:57], v[120:121] op_sel_hi:[1,0] neg_lo:[0,1] neg_hi:[0,1]
	v_exp_f32_e32 v78, v78
	v_exp_f32_e32 v79, v79
	v_exp_f32_e32 v80, v80
	v_exp_f32_e32 v81, v81
	v_exp_f32_e32 v70, v70
	v_exp_f32_e32 v71, v71
	v_exp_f32_e32 v72, v72
	v_exp_f32_e32 v73, v73
	v_exp_f32_e32 v62, v62
	v_exp_f32_e32 v63, v63
	v_exp_f32_e32 v64, v64
	v_exp_f32_e32 v65, v65
	v_exp_f32_e32 v54, v54
	v_exp_f32_e32 v55, v55
	v_exp_f32_e32 v56, v56
	v_exp_f32_e32 v57, v57
	s_nop 0
	v_pk_add_f32 v[82:83], v[78:79], v[80:81]
	v_pk_add_f32 v[84:85], v[70:71], v[72:73]
	v_pk_add_f32 v[86:87], v[62:63], v[64:65]
	v_pk_add_f32 v[88:89], v[54:55], v[56:57]
	v_pk_add_f32 v[82:83], v[82:83], v[84:85]
	v_pk_add_f32 v[86:87], v[86:87], v[88:89]
	s_nop 0
	v_pk_add_f32 v[82:83], v[82:83], v[86:87]
	s_nop 0
	v_add_f32_e32 v82, v82, v83
	v_fma_f32 v160, v160, v118, v82
	v_cvt_pk_bf16_f32 v73, v72, v73
	v_cvt_pk_bf16_f32 v72, v70, v71
	v_cvt_pk_bf16_f32 v71, v80, v81
	v_cvt_pk_bf16_f32 v70, v78, v79
	v_cvt_pk_bf16_f32 v62, v62, v63
	v_cvt_pk_bf16_f32 v63, v64, v65
	v_cvt_pk_bf16_f32 v64, v54, v55
	v_cvt_pk_bf16_f32 v65, v56, v57
	v_add_u32_e32 v115, 0xfbc, v114
	s_waitcnt lgkmcnt(0)
	ds_read2_b32 v[82:83], v115 offset1:1
	ds_read2_b32 v[84:85], v115 offset0:2 offset1:3
	ds_read2_b32 v[86:87], v115 offset0:16 offset1:17
	ds_read2_b32 v[88:89], v115 offset0:18 offset1:19
	ds_read2_b32 v[90:91], v115 offset0:32 offset1:33
	ds_read2_b32 v[92:93], v115 offset0:34 offset1:35
	ds_read2_b32 v[94:95], v115 offset0:48 offset1:49
	ds_read2_b32 v[96:97], v115 offset0:50 offset1:51
	v_mfma_f32_16x16x32_bf16 v[98:101], v[98:101], v[10:13], 0
	v_mfma_f32_16x16x32_bf16 v[102:105], v[102:105], v[10:13], 0
	v_mfma_f32_16x16x32_bf16 v[106:109], v[106:109], v[10:13], 0
	v_mfma_f32_16x16x32_bf16 v[110:113], v[110:113], v[10:13], 0
	v_mfma_f32_16x16x32_bf16 v[98:101], v[74:77], v[14:17], v[98:101]
	v_mfma_f32_16x16x32_bf16 v[102:105], v[66:69], v[14:17], v[102:105]
	v_mfma_f32_16x16x32_bf16 v[106:109], v[58:61], v[14:17], v[106:109]
	v_mfma_f32_16x16x32_bf16 v[110:113], v[50:53], v[14:17], v[110:113]
	s_waitcnt lgkmcnt(0)
	s_nop 6
	v_pk_fma_f32 v[98:99], v[98:99], s[36:37], v[82:83] op_sel_hi:[1,0,1]
	v_pk_fma_f32 v[100:101], v[100:101], s[36:37], v[84:85] op_sel_hi:[1,0,1]
	v_pk_fma_f32 v[102:103], v[102:103], s[36:37], v[86:87] op_sel_hi:[1,0,1]
	v_pk_fma_f32 v[104:105], v[104:105], s[36:37], v[88:89] op_sel_hi:[1,0,1]
	v_pk_fma_f32 v[106:107], v[106:107], s[36:37], v[90:91] op_sel_hi:[1,0,1]
	v_pk_fma_f32 v[108:109], v[108:109], s[36:37], v[92:93] op_sel_hi:[1,0,1]
	v_pk_fma_f32 v[110:111], v[110:111], s[36:37], v[94:95] op_sel_hi:[1,0,1]
	v_pk_fma_f32 v[112:113], v[112:113], s[36:37], v[96:97] op_sel_hi:[1,0,1]
	v_max3_f32 v116, v98, v99, v100
	v_max3_f32 v116, v116, v101, v102
	v_max3_f32 v116, v116, v103, v104
	v_max3_f32 v116, v116, v105, v106
	v_max3_f32 v116, v116, v107, v108
	v_max3_f32 v116, v116, v109, v110
	v_max3_f32 v116, v116, v111, v112
	v_max3_f32 v116, v116, v113, s29
	ds_bpermute_b32 v117, v0, v116
	s_waitcnt lgkmcnt(0)
	v_max_f32_e32 v116, v116, v117
	ds_bpermute_b32 v117, v149, v116
	s_waitcnt lgkmcnt(0)
	v_max_f32_e32 v116, v116, v117
	v_max_f32_e32 v121, v167, v116
	v_sub_f32_e32 v118, v167, v121
	v_exp_f32_e32 v118, v118
	v_mov_b32_e32 v167, v121
	v_mov_b32_e32 v120, v121
	v_pk_mul_f32 v[30:31], v[30:31], v[118:119] op_sel_hi:[1,0]
	v_pk_mul_f32 v[32:33], v[32:33], v[118:119] op_sel_hi:[1,0]
	v_pk_mul_f32 v[26:27], v[26:27], v[118:119] op_sel_hi:[1,0]
	v_pk_mul_f32 v[28:29], v[28:29], v[118:119] op_sel_hi:[1,0]
	v_pk_mul_f32 v[22:23], v[22:23], v[118:119] op_sel_hi:[1,0]
	v_pk_mul_f32 v[24:25], v[24:25], v[118:119] op_sel_hi:[1,0]
	v_pk_mul_f32 v[18:19], v[18:19], v[118:119] op_sel_hi:[1,0]
	v_pk_mul_f32 v[20:21], v[20:21], v[118:119] op_sel_hi:[1,0]
	v_pk_add_f32 v[98:99], v[98:99], v[120:121] op_sel_hi:[1,0] neg_lo:[0,1] neg_hi:[0,1]
	v_pk_add_f32 v[100:101], v[100:101], v[120:121] op_sel_hi:[1,0] neg_lo:[0,1] neg_hi:[0,1]
	v_pk_add_f32 v[102:103], v[102:103], v[120:121] op_sel_hi:[1,0] neg_lo:[0,1] neg_hi:[0,1]
	v_pk_add_f32 v[104:105], v[104:105], v[120:121] op_sel_hi:[1,0] neg_lo:[0,1] neg_hi:[0,1]
	v_pk_add_f32 v[106:107], v[106:107], v[120:121] op_sel_hi:[1,0] neg_lo:[0,1] neg_hi:[0,1]
	v_pk_add_f32 v[108:109], v[108:109], v[120:121] op_sel_hi:[1,0] neg_lo:[0,1] neg_hi:[0,1]
	v_pk_add_f32 v[110:111], v[110:111], v[120:121] op_sel_hi:[1,0] neg_lo:[0,1] neg_hi:[0,1]
	v_pk_add_f32 v[112:113], v[112:113], v[120:121] op_sel_hi:[1,0] neg_lo:[0,1] neg_hi:[0,1]
	v_exp_f32_e32 v98, v98
	v_exp_f32_e32 v99, v99
	v_exp_f32_e32 v100, v100
	v_exp_f32_e32 v101, v101
	v_exp_f32_e32 v102, v102
	v_exp_f32_e32 v103, v103
	v_exp_f32_e32 v104, v104
	v_exp_f32_e32 v105, v105
	v_exp_f32_e32 v106, v106
	v_exp_f32_e32 v107, v107
	v_exp_f32_e32 v108, v108
	v_exp_f32_e32 v109, v109
	v_exp_f32_e32 v110, v110
	v_exp_f32_e32 v111, v111
	v_exp_f32_e32 v112, v112
	v_exp_f32_e32 v113, v113
	s_nop 0
	v_pk_add_f32 v[82:83], v[98:99], v[100:101]
	v_pk_add_f32 v[84:85], v[102:103], v[104:105]
	v_pk_add_f32 v[86:87], v[106:107], v[108:109]
	v_pk_add_f32 v[88:89], v[110:111], v[112:113]
	v_pk_add_f32 v[82:83], v[82:83], v[84:85]
	v_pk_add_f32 v[86:87], v[86:87], v[88:89]
	s_nop 0
	v_pk_add_f32 v[82:83], v[82:83], v[86:87]
	s_nop 0
	v_add_f32_e32 v82, v82, v83
	v_fma_f32 v161, v161, v118, v82
	v_cvt_pk_bf16_f32 v105, v104, v105
	v_cvt_pk_bf16_f32 v104, v102, v103
	v_cvt_pk_bf16_f32 v103, v100, v101
	v_cvt_pk_bf16_f32 v102, v98, v99
	v_cvt_pk_bf16_f32 v106, v106, v107
	v_cvt_pk_bf16_f32 v107, v108, v109
	v_cvt_pk_bf16_f32 v108, v110, v111
	v_cvt_pk_bf16_f32 v109, v112, v113
.Lnw_pv:
	v_add3_u32 v114, s16, v217, v219
	v_add_u32_e32 v115, v114, v220
	v_add_u32_e32 v116, v114, v221
	v_add_u32_e32 v117, v114, v222
	v_add_u32_e32 v119, v114, v223
	ds_read_b64_tr_b16 v[82:83], v115 offset:40960
	ds_read_b64_tr_b16 v[84:85], v115 offset:43008
	ds_read_b64_tr_b16 v[86:87], v116 offset:40960
	ds_read_b64_tr_b16 v[88:89], v116 offset:43008
	ds_read_b64_tr_b16 v[90:91], v117 offset:40960
	ds_read_b64_tr_b16 v[92:93], v117 offset:43008
	ds_read_b64_tr_b16 v[94:95], v119 offset:40960
	ds_read_b64_tr_b16 v[96:97], v119 offset:43008
	s_waitcnt lgkmcnt(6)
	v_mfma_f32_16x16x32_bf16 v[46:49], v[82:85], v[70:73], v[46:49]
	v_mfma_f32_16x16x32_bf16 v[30:33], v[82:85], v[102:105], v[30:33]
	ds_read_b64_tr_b16 v[74:75], v115 offset:45056
	ds_read_b64_tr_b16 v[76:77], v115 offset:47104
	s_waitcnt lgkmcnt(6)
	v_mfma_f32_16x16x32_bf16 v[42:45], v[86:89], v[70:73], v[42:45]
	v_mfma_f32_16x16x32_bf16 v[26:29], v[86:89], v[102:105], v[26:29]
	ds_read_b64_tr_b16 v[66:67], v116 offset:45056
	ds_read_b64_tr_b16 v[68:69], v116 offset:47104
	s_waitcnt lgkmcnt(6)
	v_mfma_f32_16x16x32_bf16 v[38:41], v[90:93], v[70:73], v[38:41]
	v_mfma_f32_16x16x32_bf16 v[22:25], v[90:93], v[102:105], v[22:25]
	ds_read_b64_tr_b16 v[58:59], v117 offset:45056
	ds_read_b64_tr_b16 v[60:61], v117 offset:47104
	s_waitcnt lgkmcnt(6)
	v_mfma_f32_16x16x32_bf16 v[34:37], v[94:97], v[70:73], v[34:37]
	v_mfma_f32_16x16x32_bf16 v[18:21], v[94:97], v[102:105], v[18:21]
	ds_read_b64_tr_b16 v[50:51], v119 offset:45056
	ds_read_b64_tr_b16 v[52:53], v119 offset:47104
	s_waitcnt lgkmcnt(6)
	v_mfma_f32_16x16x32_bf16 v[46:49], v[74:77], v[62:65], v[46:49]
	v_mfma_f32_16x16x32_bf16 v[30:33], v[74:77], v[106:109], v[30:33]
	s_waitcnt lgkmcnt(4)
	v_mfma_f32_16x16x32_bf16 v[42:45], v[66:69], v[62:65], v[42:45]
	v_mfma_f32_16x16x32_bf16 v[26:29], v[66:69], v[106:109], v[26:29]
	s_waitcnt lgkmcnt(2)
	v_mfma_f32_16x16x32_bf16 v[38:41], v[58:61], v[62:65], v[38:41]
	v_mfma_f32_16x16x32_bf16 v[22:25], v[58:61], v[106:109], v[22:25]
	s_waitcnt lgkmcnt(0)
	v_mfma_f32_16x16x32_bf16 v[34:37], v[50:53], v[62:65], v[34:37]
	v_mfma_f32_16x16x32_bf16 v[18:21], v[50:53], v[106:109], v[18:21]
	s_xor_b64 s[42:43], s[72:73], -1
	s_mov_b32 s25, 1
	s_mov_b64 s[72:73], 0
	s_and_b64 vcc, exec, s[42:43]
	s_cbranch_vccz .LBB0_287
